# P8 conversion: next ticket's atomic issued mid-tile (after the tile's loads are consumed) so its round trip hides under the store phase
# speedup vs baseline: 1.0115x; 1.0015x over previous
; DEVINL void tr_tile(const float* __restrict__ src, int ldsrc, int nvalid, int k0, int n0,
;                     u16* __restrict__ dst, int lddst, int grp, int gstride, int goff) {
;     ...
; #pragma unroll
;   for (int i = 0; i < 8; ++i) {
;     int f = tid + i * 512; int r = f >> 6, c4 = (f & 63) * 4;
;     int n = n0 + c4;
;     v[i] = make_float4(0.f, 0.f, 0.f, 0.f);
;     if (n < nvalid) {
;       const f32x4 q = __builtin_nontemporal_load((const f32x4*)(src + (long)(k0 + r) * ldsrc + n));
;       v[i] = make_float4(q[0], q[1], q[2], q[3]);
;     }
;   }
; #pragma unroll
;   for (int i = 0; i < 8; ++i) {
;     int f = tid + i * 512; int r = f >> 6, c4 = (f & 63) * 4;
;     float* tp = tile + r * 257 + c4;
;     tp[0] = v[i].x; tp[1] = v[i].y; tp[2] = v[i].z; tp[3] = v[i].w;
;   }
; DEVINL void phase8(const Params& p) {
;     ...
;       if (tid == 0) *slot = (int)atomicAdd(ticket, 1u);
;       __syncthreads();
;       const int t = *slot;
;       if (t >= 16 * 128 * 3) break;
;       const int which = t / (16 * 128), r = t % (16 * 128), e = r >> 7, tt = r & 127;
;       if (which < 2) {
;         const float* src = (which ? p.w3 : p.w1) + (long)e * 2048 * 1024;
;         int kt = tt & 31, ntile = tt >> 5;
;         tr_tile(src, 1024, 1024, kt * 64, ntile * 256, (u16*)(ws + O_W13T) + (long)e * 2048 * 2048, 2048, 128, 256, which * 128);
;       } else {
;         const float* src = p.w2 + (long)e * 1024 * 2048;
;         int kt = tt & 15, ntile = tt >> 4;
;         tr_tile(src, 2048, 2048, kt * 64, ntile * 256, (u16*)(ws + O_W2T) + (long)e * 2048 * 1024, 1024, 1 << 30, 0, 0);
.LBB0_906:
	s_and_saveexec_b64 s[12:13], vcc
	s_cbranch_execz .LBB0_910
	s_waitcnt vmcnt(0)
	v_mov_b32_e32 v0, v60
	v_mov_b32_e32 v2, s3
	ds_write_b32 v2, v0
	s_waitcnt lgkmcnt(0)
.LBB0_910:
	s_or_b64 exec, exec, s[12:13]
	v_mov_b32_e32 v2, s3
	s_waitcnt lgkmcnt(0)
	s_barrier
	ds_read_b32 v3, v2
	s_mov_b64 s[14:15], -1
	s_waitcnt lgkmcnt(0)
	v_cmp_gt_i32_e64 s[0:1], s4, v3
	s_and_saveexec_b64 s[12:13], s[0:1]
	s_cbranch_execz .LBB0_905
	v_ashrrev_i32_e32 v0, 31, v3
	v_lshrrev_b32_e32 v0, 21, v0
	v_add_u32_e32 v0, v3, v0
	v_ashrrev_i32_e32 v4, 11, v0
	v_mul_i32_i24_e32 v0, 0x800, v4
	v_sub_u32_e32 v0, v3, v0
	v_ashrrev_i32_e32 v2, 7, v0
	v_cmp_lt_i32_e64 s[0:1], s18, v3
	v_lshlrev_b32_e32 v5, 6, v0
	s_and_saveexec_b64 s[14:15], s[0:1]
	s_xor_b64 s[0:1], exec, s[14:15]
	s_cbranch_execz .LBB0_913
	v_lshlrev_b32_e32 v0, 4, v0
	v_mov_b32_e32 v48, v189
	v_and_b32_e32 v47, 0x700, v0
	v_mov_b32_e32 v3, v1
	v_lshlrev_b32_e32 v0, 2, v48
	v_and_b32_e32 v36, 0xfc, v0
	v_lshlrev_b64 v[6:7], 23, v[2:3]
	v_and_b32_e32 v46, 0x3c0, v5
	v_or_b32_e32 v0, v36, v47
	v_ashrrev_i32_e32 v37, 6, v48
	v_lshl_add_u64 v[6:7], s[84:85], 0, v[6:7]
	v_lshlrev_b32_e32 v0, 2, v0
	v_add_u32_e32 v4, v37, v46
	v_lshl_add_u64 v[32:33], v[6:7], 0, v[0:1]
	v_ashrrev_i32_e32 v5, 31, v4
	v_add_u32_e32 v0, 0x200, v48
	v_lshlrev_b64 v[4:5], 13, v[4:5]
	v_ashrrev_i32_e32 v38, 6, v0
	v_lshl_add_u64 v[12:13], v[32:33], 0, v[4:5]
	v_add_u32_e32 v4, v38, v46
	v_ashrrev_i32_e32 v5, 31, v4
	v_add_u32_e32 v0, 0x400, v48
	v_lshlrev_b64 v[4:5], 13, v[4:5]
	v_ashrrev_i32_e32 v40, 6, v0
	v_lshl_add_u64 v[14:15], v[32:33], 0, v[4:5]
	global_load_dwordx4 v[4:7], v[12:13], off nt
	global_load_dwordx4 v[8:11], v[14:15], off nt
	v_add_u32_e32 v12, v40, v46
	v_ashrrev_i32_e32 v13, 31, v12
	v_add_u32_e32 v0, 0x600, v48
	v_lshlrev_b64 v[12:13], 13, v[12:13]
	v_ashrrev_i32_e32 v42, 6, v0
	v_lshl_add_u64 v[20:21], v[32:33], 0, v[12:13]
	v_add_u32_e32 v12, v42, v46
	v_ashrrev_i32_e32 v13, 31, v12
	v_add_u32_e32 v0, 0x800, v48
	v_lshlrev_b64 v[12:13], 13, v[12:13]
	v_ashrrev_i32_e32 v44, 6, v0
	v_lshl_add_u64 v[22:23], v[32:33], 0, v[12:13]
	global_load_dwordx4 v[12:15], v[20:21], off nt
	global_load_dwordx4 v[16:19], v[22:23], off nt
	v_add_u32_e32 v20, v44, v46
	v_ashrrev_i32_e32 v21, 31, v20
	v_add_u32_e32 v0, 0xa00, v48
	v_lshlrev_b64 v[20:21], 13, v[20:21]
	v_ashrrev_i32_e32 v49, 6, v0
	v_lshl_add_u64 v[28:29], v[32:33], 0, v[20:21]
	v_add_u32_e32 v20, v49, v46
	v_ashrrev_i32_e32 v21, 31, v20
	v_add_u32_e32 v0, 0xc00, v48
	v_lshlrev_b64 v[20:21], 13, v[20:21]
	v_ashrrev_i32_e32 v50, 6, v0
	v_add_u32_e32 v0, 0xe00, v48
	v_lshl_add_u64 v[30:31], v[32:33], 0, v[20:21]
	global_load_dwordx4 v[20:23], v[28:29], off nt
	global_load_dwordx4 v[24:27], v[30:31], off nt
	v_add_u32_e32 v28, v50, v46
	v_ashrrev_i32_e32 v51, 6, v0
	v_ashrrev_i32_e32 v29, 31, v28
	v_add_u32_e32 v34, v51, v46
	v_lshlrev_b64 v[28:29], 13, v[28:29]
	v_ashrrev_i32_e32 v35, 31, v34
	v_lshl_add_u64 v[28:29], v[32:33], 0, v[28:29]
	v_lshlrev_b64 v[34:35], 13, v[34:35]
	global_load_dwordx4 v[28:31], v[28:29], off nt
	v_lshl_add_u64 v[32:33], v[32:33], 0, v[34:35]
	global_load_dwordx4 v[32:35], v[32:33], off nt
	v_lshl_add_u32 v0, v36, 2, 16
	v_mad_u64_u32 v[36:37], s[14:15], v37, s19, v[0:1]
	v_mad_u64_u32 v[38:39], s[14:15], v38, s19, v[0:1]
	v_mad_u64_u32 v[40:41], s[14:15], v40, s19, v[0:1]
	v_mad_u64_u32 v[42:43], s[14:15], v42, s19, v[0:1]
	v_mad_u64_u32 v[44:45], s[14:15], v44, s19, v[0:1]
	v_lshlrev_b64 v[2:3], 22, v[2:3]
	v_lshl_add_u64 v[2:3], s[10:11], 0, v[2:3]
	s_waitcnt vmcnt(7)
	ds_write2_b32 v36, v4, v5 offset1:1
	ds_write2_b32 v36, v6, v7 offset0:2 offset1:3
	s_waitcnt vmcnt(6)
	ds_write2_b32 v38, v8, v9 offset1:1
	ds_write2_b32 v38, v10, v11 offset0:2 offset1:3
	s_waitcnt vmcnt(5)
	ds_write2_b32 v40, v12, v13 offset1:1
	ds_write2_b32 v40, v14, v15 offset0:2 offset1:3
	s_waitcnt vmcnt(4)
	ds_write2_b32 v42, v16, v17 offset1:1
	ds_write2_b32 v42, v18, v19 offset0:2 offset1:3
	s_waitcnt vmcnt(3)
	ds_write2_b32 v44, v20, v21 offset1:1
	ds_write2_b32 v44, v22, v23 offset0:2 offset1:3
	v_mad_u64_u32 v[4:5], s[14:15], v49, s19, v[0:1]
	s_waitcnt vmcnt(2)
	ds_write2_b32 v4, v24, v25 offset1:1
	ds_write2_b32 v4, v26, v27 offset0:2 offset1:3
	v_mad_u64_u32 v[4:5], s[14:15], v50, s19, v[0:1]
	s_waitcnt vmcnt(1)
	ds_write2_b32 v4, v28, v29 offset1:1
	ds_write2_b32 v4, v30, v31 offset0:2 offset1:3
	v_mad_u64_u32 v[4:5], s[14:15], v51, s19, v[0:1]
	s_waitcnt vmcnt(0)
	ds_write2_b32 v4, v32, v33 offset1:1
	ds_write2_b32 v4, v34, v35 offset0:2 offset1:3
	v_lshlrev_b32_e32 v4, 5, v48
	v_ashrrev_i32_e32 v0, 1, v48
	v_and_b32_e32 v6, 32, v4
	v_mul_u32_u24_e32 v4, 0x404, v6
	v_lshlrev_b32_e32 v5, 2, v0
	v_add_u32_e32 v0, v0, v47
	v_add3_u32 v8, 16, v4, v5
	v_ashrrev_i32_e32 v4, 31, v0
	v_lshrrev_b32_e32 v4, 2, v4
	v_add_u32_e32 v4, v0, v4
	v_and_b32_e32 v4, -2.0, v4
	v_sub_u32_e32 v4, v0, v4
	v_ashrrev_i32_e32 v5, 31, v4
	v_lshlrev_b64 v[4:5], 11, v[4:5]
	s_waitcnt lgkmcnt(0)
	s_and_saveexec_b64 s[16:17], vcc
	s_cbranch_execz .Lp8_pfa
	v_mov_b32_e32 v61, 1
	global_atomic_add v60, v1, v61, s[96:97] sc0
; DEVINL void tr_tile(const float* __restrict__ src, int ldsrc, int nvalid, int k0, int n0,
;                     u16* __restrict__ dst, int lddst, int grp, int gstride, int goff) {
;     ...
;   {
;     const int n = tid >> 1, kc = (tid & 1) * 32;
;     const float* tp = tile + kc * 257 + n;
;     const int nn = n0 + n;
;     const long row = (long)(nn / grp) * gstride + (nn % grp) + goff;
;     uint4* dp = (uint4*)(dst + row * lddst + k0 + kc);
; #pragma unroll
;     for (int q = 0; q < 4; ++q) {
;       uint4 o;
;       o.x = pk2(tp[(q * 8 + 0) * 257], tp[(q * 8 + 1) * 257]);
;       o.y = pk2(tp[(q * 8 + 2) * 257], tp[(q * 8 + 3) * 257]);
;       o.z = pk2(tp[(q * 8 + 4) * 257], tp[(q * 8 + 5) * 257]);
;       o.w = pk2(tp[(q * 8 + 6) * 257], tp[(q * 8 + 7) * 257]);
;       dp[q] = o;
;     }
;   }
.Lp8_pfa:
	s_or_b64 exec, exec, s[16:17]
	s_barrier
	v_lshl_add_u64 v[2:3], v[2:3], 0, v[4:5]
	ds_read_b32 v4, v8
	ds_read_b32 v5, v8 offset:1028
	ds_read_b32 v9, v8 offset:2056
	ds_read_b32 v10, v8 offset:3084
	ds_read_b32 v11, v8 offset:4112
	ds_read_b32 v12, v8 offset:5140
	ds_read_b32 v13, v8 offset:6168
	ds_read_b32 v14, v8 offset:7196
	v_lshlrev_b32_e32 v0, 1, v46
	v_lshl_add_u64 v[2:3], v[2:3], 0, v[0:1]
	v_lshlrev_b32_e32 v0, 1, v6
	v_lshl_add_u64 v[6:7], v[2:3], 0, v[0:1]
	s_waitcnt lgkmcnt(6)
	v_cvt_pk_bf16_f32 v2, v4, v5
	s_waitcnt lgkmcnt(4)
	v_cvt_pk_bf16_f32 v3, v9, v10
	s_waitcnt lgkmcnt(2)
	v_cvt_pk_bf16_f32 v4, v11, v12
	s_waitcnt lgkmcnt(0)
	v_cvt_pk_bf16_f32 v5, v13, v14
	ds_read_b32 v0, v8 offset:8224
	ds_read_b32 v9, v8 offset:9252
	ds_read_b32 v10, v8 offset:10280
	ds_read_b32 v11, v8 offset:11308
	ds_read_b32 v12, v8 offset:12336
	ds_read_b32 v13, v8 offset:13364
	ds_read_b32 v14, v8 offset:14392
	ds_read_b32 v15, v8 offset:15420
	global_store_dwordx4 v[6:7], v[2:5], off
	s_waitcnt lgkmcnt(6)
	s_nop 0
	v_cvt_pk_bf16_f32 v2, v0, v9
	s_waitcnt lgkmcnt(4)
	v_cvt_pk_bf16_f32 v3, v10, v11
	s_waitcnt lgkmcnt(2)
	v_cvt_pk_bf16_f32 v4, v12, v13
	s_waitcnt lgkmcnt(0)
	v_cvt_pk_bf16_f32 v5, v14, v15
	ds_read_b32 v0, v8 offset:16448
	ds_read_b32 v9, v8 offset:17476
	ds_read_b32 v10, v8 offset:18504
	ds_read_b32 v11, v8 offset:19532
	ds_read_b32 v12, v8 offset:20560
	ds_read_b32 v13, v8 offset:21588
	ds_read_b32 v14, v8 offset:22616
	ds_read_b32 v15, v8 offset:23644
	global_store_dwordx4 v[6:7], v[2:5], off offset:16
	s_waitcnt lgkmcnt(6)
	s_nop 0
	v_cvt_pk_bf16_f32 v2, v0, v9
	s_waitcnt lgkmcnt(4)
	v_cvt_pk_bf16_f32 v3, v10, v11
	s_waitcnt lgkmcnt(2)
	v_cvt_pk_bf16_f32 v4, v12, v13
	s_waitcnt lgkmcnt(0)
	v_cvt_pk_bf16_f32 v5, v14, v15
	ds_read_b32 v0, v8 offset:24672
	ds_read_b32 v9, v8 offset:25700
	ds_read_b32 v10, v8 offset:26728
	ds_read_b32 v11, v8 offset:27756
	ds_read_b32 v12, v8 offset:28784
	ds_read_b32 v13, v8 offset:29812
	ds_read_b32 v14, v8 offset:30840
	ds_read_b32 v8, v8 offset:31868
	global_store_dwordx4 v[6:7], v[2:5], off offset:32
	s_waitcnt lgkmcnt(6)
	s_nop 0
	v_cvt_pk_bf16_f32 v2, v0, v9
	s_waitcnt lgkmcnt(4)
	v_cvt_pk_bf16_f32 v3, v10, v11
	s_waitcnt lgkmcnt(2)
	v_cvt_pk_bf16_f32 v4, v12, v13
	s_waitcnt lgkmcnt(0)
	v_cvt_pk_bf16_f32 v5, v14, v8
	global_store_dwordx4 v[6:7], v[2:5], off offset:48
	s_barrier
.LBB0_913:
	s_andn2_saveexec_b64 s[14:15], s[0:1]
	s_cbranch_execz .LBB0_904
; DEVINL int otid() { int t = threadIdx.x; asm volatile("" : "+v"(t)); return t; }
; DEVINL void tr_tile(const float* __restrict__ src, int ldsrc, int nvalid, int k0, int n0,
;                     u16* __restrict__ dst, int lddst, int grp, int gstride, int goff) {
;   float* tile = (float*)dynsmem;
;   const int tid = otid();
;   float4 v[8];
; #pragma unroll
;   for (int i = 0; i < 8; ++i) {
;     int f = tid + i * 512; int r = f >> 6, c4 = (f & 63) * 4;
;     int n = n0 + c4;
;     v[i] = make_float4(0.f, 0.f, 0.f, 0.f);
;     if (n < nvalid) {
;       const f32x4 q = __builtin_nontemporal_load((const f32x4*)(src + (long)(k0 + r) * ldsrc + n));
;       v[i] = make_float4(q[0], q[1], q[2], q[3]);
;     }
;   }
; #pragma unroll
;   for (int i = 0; i < 8; ++i) {
;     int f = tid + i * 512; int r = f >> 6, c4 = (f & 63) * 4;
;     float* tp = tile + r * 257 + c4;
;     tp[0] = v[i].x; tp[1] = v[i].y; tp[2] = v[i].z; tp[3] = v[i].w;
;   }
;   __syncthreads();
;   {
;     const int n = tid >> 1, kc = (tid & 1) * 32;
;     const float* tp = tile + kc * 257 + n;
;     const int nn = n0 + n;
;     const long row = (long)(nn / grp) * gstride + (nn % grp) + goff;
;     uint4* dp = (uint4*)(dst + row * lddst + k0 + kc);
; #pragma unroll
;     for (int q = 0; q < 4; ++q) {
;       uint4 o;
;       o.x = pk2(tp[(q * 8 + 0) * 257], tp[(q * 8 + 1) * 257]);
;       o.y = pk2(tp[(q * 8 + 2) * 257], tp[(q * 8 + 3) * 257]);
;       o.z = pk2(tp[(q * 8 + 4) * 257], tp[(q * 8 + 5) * 257]);
;       o.w = pk2(tp[(q * 8 + 6) * 257], tp[(q * 8 + 7) * 257]);
;       dp[q] = o;
;     }
;   }
;   __syncthreads();
; DEVINL void phase8(const Params& p) {
;     ...
;       if (which < 2) {
;         const float* src = (which ? p.w3 : p.w1) + (long)e * 2048 * 1024;
;         int kt = tt & 31, ntile = tt >> 5;
;         tr_tile(src, 1024, 1024, kt * 64, ntile * 256, (u16*)(ws + O_W13T) + (long)e * 2048 * 2048, 2048, 128, 256, which * 128);
	v_add_u32_e32 v3, 0x7ff, v3
	v_mov_b32_e32 v6, s83
	v_mov_b32_e32 v7, s81
	v_cmp_gt_u32_e64 s[0:1], s18, v3
	v_lshlrev_b32_e32 v0, 3, v0
	v_mov_b32_e32 v45, v189
	v_cndmask_b32_e64 v7, v6, v7, s[0:1]
	v_mov_b32_e32 v3, s82
	v_mov_b32_e32 v6, s80
	v_and_b32_e32 v44, 0x7c0, v5
	v_and_b32_e32 v5, 0x300, v0
	v_cndmask_b32_e64 v6, v3, v6, s[0:1]
	v_lshlrev_b32_e32 v0, 2, v45
	v_ashrrev_i32_e32 v3, 31, v2
	v_and_b32_e32 v38, 0xfc, v0
	v_lshlrev_b64 v[2:3], 23, v[2:3]
	v_or_b32_e32 v0, v38, v5
	v_lshl_add_u64 v[6:7], v[6:7], 0, v[2:3]
	v_lshlrev_b32_e32 v0, 2, v0
	v_ashrrev_i32_e32 v39, 6, v45
	v_lshl_add_u64 v[34:35], v[6:7], 0, v[0:1]
	v_add_u32_e32 v6, v39, v44
	v_ashrrev_i32_e32 v7, 31, v6
	v_add_u32_e32 v0, 0x200, v45
	v_lshlrev_b64 v[6:7], 12, v[6:7]
	v_ashrrev_i32_e32 v40, 6, v0
	v_lshl_add_u64 v[14:15], v[34:35], 0, v[6:7]
	v_add_u32_e32 v6, v40, v44
	v_ashrrev_i32_e32 v7, 31, v6
	v_add_u32_e32 v0, 0x400, v45
	v_lshlrev_b64 v[6:7], 12, v[6:7]
	v_ashrrev_i32_e32 v42, 6, v0
	v_lshl_add_u64 v[16:17], v[34:35], 0, v[6:7]
	global_load_dwordx4 v[6:9], v[14:15], off nt
	global_load_dwordx4 v[10:13], v[16:17], off nt
	v_add_u32_e32 v14, v42, v44
	v_ashrrev_i32_e32 v15, 31, v14
	v_add_u32_e32 v0, 0x600, v45
	v_lshlrev_b64 v[14:15], 12, v[14:15]
	v_ashrrev_i32_e32 v46, 6, v0
	v_lshl_add_u64 v[22:23], v[34:35], 0, v[14:15]
	v_add_u32_e32 v14, v46, v44
	v_ashrrev_i32_e32 v15, 31, v14
	v_add_u32_e32 v0, 0x800, v45
	v_lshlrev_b64 v[14:15], 12, v[14:15]
	v_ashrrev_i32_e32 v47, 6, v0
	v_lshl_add_u64 v[24:25], v[34:35], 0, v[14:15]
	global_load_dwordx4 v[14:17], v[22:23], off nt
	global_load_dwordx4 v[18:21], v[24:25], off nt
	v_add_u32_e32 v22, v47, v44
	v_ashrrev_i32_e32 v23, 31, v22
	v_add_u32_e32 v0, 0xa00, v45
	v_lshlrev_b64 v[22:23], 12, v[22:23]
	v_ashrrev_i32_e32 v48, 6, v0
	v_lshl_add_u64 v[30:31], v[34:35], 0, v[22:23]
	v_add_u32_e32 v22, v48, v44
	v_ashrrev_i32_e32 v23, 31, v22
	v_add_u32_e32 v0, 0xc00, v45
	v_lshlrev_b64 v[22:23], 12, v[22:23]
	v_ashrrev_i32_e32 v49, 6, v0
	v_lshl_add_u64 v[32:33], v[34:35], 0, v[22:23]
	global_load_dwordx4 v[22:25], v[30:31], off nt
	global_load_dwordx4 v[26:29], v[32:33], off nt
	v_add_u32_e32 v30, v49, v44
	v_add_u32_e32 v0, 0xe00, v45
	v_ashrrev_i32_e32 v31, 31, v30
	v_ashrrev_i32_e32 v50, 6, v0
	v_lshlrev_b64 v[30:31], 12, v[30:31]
	v_add_u32_e32 v36, v50, v44
	v_lshl_add_u64 v[30:31], v[34:35], 0, v[30:31]
	v_ashrrev_i32_e32 v37, 31, v36
	global_load_dwordx4 v[30:33], v[30:31], off nt
	v_lshlrev_b64 v[36:37], 12, v[36:37]
	v_lshl_add_u64 v[34:35], v[34:35], 0, v[36:37]
	global_load_dwordx4 v[34:37], v[34:35], off nt
	v_lshl_add_u32 v0, v38, 2, 16
	v_mad_u64_u32 v[38:39], s[0:1], v39, s19, v[0:1]
	v_mad_u64_u32 v[40:41], s[0:1], v40, s19, v[0:1]
	v_mad_u64_u32 v[42:43], s[0:1], v42, s19, v[0:1]
	v_lshl_add_u64 v[2:3], s[8:9], 0, v[2:3]
	s_waitcnt vmcnt(7)
	ds_write2_b32 v38, v6, v7 offset1:1
	ds_write2_b32 v38, v8, v9 offset0:2 offset1:3
	s_waitcnt vmcnt(6)
	ds_write2_b32 v40, v10, v11 offset1:1
	ds_write2_b32 v40, v12, v13 offset0:2 offset1:3
	s_waitcnt vmcnt(5)
	ds_write2_b32 v42, v14, v15 offset1:1
	ds_write2_b32 v42, v16, v17 offset0:2 offset1:3
	v_mad_u64_u32 v[6:7], s[0:1], v46, s19, v[0:1]
	s_waitcnt vmcnt(4)
	ds_write2_b32 v6, v18, v19 offset1:1
	ds_write2_b32 v6, v20, v21 offset0:2 offset1:3
	v_mad_u64_u32 v[6:7], s[0:1], v47, s19, v[0:1]
	s_waitcnt vmcnt(3)
	ds_write2_b32 v6, v22, v23 offset1:1
	ds_write2_b32 v6, v24, v25 offset0:2 offset1:3
	v_mad_u64_u32 v[6:7], s[0:1], v48, s19, v[0:1]
	s_waitcnt vmcnt(2)
	ds_write2_b32 v6, v26, v27 offset1:1
	ds_write2_b32 v6, v28, v29 offset0:2 offset1:3
	v_mad_u64_u32 v[6:7], s[0:1], v49, s19, v[0:1]
	s_waitcnt vmcnt(1)
	ds_write2_b32 v6, v30, v31 offset1:1
	ds_write2_b32 v6, v32, v33 offset0:2 offset1:3
	v_mad_u64_u32 v[6:7], s[0:1], v50, s19, v[0:1]
	v_ashrrev_i32_e32 v0, 1, v45
	v_lshlrev_b32_e32 v7, 2, v0
	v_add_u32_e32 v0, v0, v5
	s_waitcnt vmcnt(0)
	ds_write2_b32 v6, v34, v35 offset1:1
	ds_write2_b32 v6, v36, v37 offset0:2 offset1:3
	v_lshlrev_b32_e32 v6, 5, v45
	v_ashrrev_i32_e32 v5, 31, v0
	v_and_b32_e32 v8, 32, v6
	v_lshrrev_b32_e32 v5, 25, v5
	v_mul_u32_u24_e32 v6, 0x404, v8
	v_add_u32_e32 v5, v0, v5
	v_add3_u32 v9, 16, v6, v7
	v_ashrrev_i32_e32 v6, 7, v5
	v_and_b32_e32 v5, 0xffffff80, v5
	v_sub_u32_e32 v0, v0, v5
	v_ashrrev_i32_e32 v7, 31, v6
	v_lshl_add_u32 v4, v4, 7, v0
	v_ashrrev_i32_e32 v5, 31, v4
	v_lshlrev_b64 v[6:7], 20, v[6:7]
	v_lshl_add_u64 v[2:3], v[2:3], 0, v[6:7]
	v_lshlrev_b64 v[4:5], 12, v[4:5]
	v_lshl_add_u64 v[2:3], v[2:3], 0, v[4:5]
	v_lshlrev_b32_e32 v0, 1, v44
	s_waitcnt lgkmcnt(0)
	s_and_saveexec_b64 s[16:17], vcc
	s_cbranch_execz .Lp8_pfb
	v_mov_b32_e32 v61, 1
	global_atomic_add v60, v1, v61, s[96:97] sc0
.Lp8_pfb:
	s_or_b64 exec, exec, s[16:17]
	s_barrier
	v_lshl_add_u64 v[2:3], v[2:3], 0, v[0:1]
	v_lshlrev_b32_e32 v0, 1, v8
	ds_read_b32 v4, v9
	ds_read_b32 v5, v9 offset:1028
	ds_read_b32 v8, v9 offset:2056
	ds_read_b32 v10, v9 offset:3084
	ds_read_b32 v11, v9 offset:4112
	ds_read_b32 v12, v9 offset:5140
	ds_read_b32 v13, v9 offset:6168
	ds_read_b32 v14, v9 offset:7196
	v_lshl_add_u64 v[6:7], v[2:3], 0, v[0:1]
	s_waitcnt lgkmcnt(6)
	v_cvt_pk_bf16_f32 v2, v4, v5
	s_waitcnt lgkmcnt(4)
	v_cvt_pk_bf16_f32 v3, v8, v10
	s_waitcnt lgkmcnt(2)
	v_cvt_pk_bf16_f32 v4, v11, v12
	s_waitcnt lgkmcnt(0)
	v_cvt_pk_bf16_f32 v5, v13, v14
	ds_read_b32 v0, v9 offset:8224
	ds_read_b32 v8, v9 offset:9252
	ds_read_b32 v10, v9 offset:10280
	ds_read_b32 v11, v9 offset:11308
	ds_read_b32 v12, v9 offset:12336
	ds_read_b32 v13, v9 offset:13364
	ds_read_b32 v14, v9 offset:14392
	ds_read_b32 v15, v9 offset:15420
	global_store_dwordx4 v[6:7], v[2:5], off
	s_waitcnt lgkmcnt(6)
	s_nop 0
	v_cvt_pk_bf16_f32 v2, v0, v8
	s_waitcnt lgkmcnt(4)
	v_cvt_pk_bf16_f32 v3, v10, v11
	s_waitcnt lgkmcnt(2)
	v_cvt_pk_bf16_f32 v4, v12, v13
	s_waitcnt lgkmcnt(0)
	v_cvt_pk_bf16_f32 v5, v14, v15
	ds_read_b32 v0, v9 offset:16448
	ds_read_b32 v8, v9 offset:17476
	ds_read_b32 v10, v9 offset:18504
	ds_read_b32 v11, v9 offset:19532
	ds_read_b32 v12, v9 offset:20560
	ds_read_b32 v13, v9 offset:21588
	ds_read_b32 v14, v9 offset:22616
	ds_read_b32 v15, v9 offset:23644
	global_store_dwordx4 v[6:7], v[2:5], off offset:16
	s_waitcnt lgkmcnt(6)
	s_nop 0
	v_cvt_pk_bf16_f32 v2, v0, v8
	s_waitcnt lgkmcnt(4)
	v_cvt_pk_bf16_f32 v3, v10, v11
	s_waitcnt lgkmcnt(2)
	v_cvt_pk_bf16_f32 v4, v12, v13
	s_waitcnt lgkmcnt(0)
	v_cvt_pk_bf16_f32 v5, v14, v15
	ds_read_b32 v0, v9 offset:24672
	ds_read_b32 v8, v9 offset:25700
	ds_read_b32 v10, v9 offset:26728
	ds_read_b32 v11, v9 offset:27756
	ds_read_b32 v12, v9 offset:28784
	ds_read_b32 v13, v9 offset:29812
	ds_read_b32 v14, v9 offset:30840
	ds_read_b32 v9, v9 offset:31868
	global_store_dwordx4 v[6:7], v[2:5], off offset:32
	s_waitcnt lgkmcnt(6)
	s_nop 0
	v_cvt_pk_bf16_f32 v2, v0, v8
	s_waitcnt lgkmcnt(4)
	v_cvt_pk_bf16_f32 v3, v10, v11
	s_waitcnt lgkmcnt(2)
	v_cvt_pk_bf16_f32 v4, v12, v13
	s_waitcnt lgkmcnt(0)
	v_cvt_pk_bf16_f32 v5, v14, v9
	global_store_dwordx4 v[6:7], v[2:5], off offset:48
	s_barrier
	s_branch .LBB0_904
